# attention epilogues: 16 dwordx2 row-per-lane stores widened to 8 dwordx4 via v_permlane32_swap pairs (guide 7.3 / T21)
# speedup vs baseline: 1.0336x; 1.0112x over previous
; __device__ __forceinline__ unsigned cvt_pk_bf16(float lo, float hi) { unsigned r; asm volatile("v_cvt_pk_bf16_f32 %0, %1, %2" : "=v"(r) : "v"(lo), "v"(hi)); return r; }
; __device__ __forceinline__ void attn_win(unsigned char* lds, const int unit, const bf16_t* __restrict__ QKG, const bf16_t* __restrict__ Vt, bf16_t* __restrict__ Oout, const float* __restrict__ sink) {
;     ...
;     const float lt = l_run + __shfl_xor(l_run, 32), inv = 1.0f / lt;
;     bf16_t* op = Oout + (size_t)(b * SEQ + qtok) * 1024 + 128 * head + 4 * hi;
; #pragma unroll
;     for (int db = 0; db < 4; ++db)
; #pragma unroll
;         for (int rg = 0; rg < 4; ++rg) { u32x2 w; w.x = cvt_pk_bf16(o[db][4 * rg] * inv, o[db][4 * rg + 1] * inv); w.y = cvt_pk_bf16(o[db][4 * rg + 2] * inv, o[db][4 * rg + 3] * inv);
;             *(u32x2*)(op + 32 * db + 8 * rg) = w; }
.LBB0_565:
	v_and_b32_e32 v2, 64, v206
	v_xor_b32_e32 v0, 32, v206
	v_add_u32_e32 v2, 64, v2
	v_cmp_lt_i32_e32 vcc, v0, v2
	v_lshlrev_b64 v[2:3], 11, v[182:183]
	v_lshl_add_u64 v[2:3], s[58:59], 0, v[2:3]
	v_cndmask_b32_e32 v0, v206, v0, vcc
	v_lshlrev_b32_e32 v0, 2, v0
	ds_bpermute_b32 v0, v0, v177
	v_lshl_add_u64 v[2:3], s[0:1], 1, v[2:3]
	s_waitcnt lgkmcnt(0)
	v_add_f32_e32 v0, v177, v0
	v_div_scale_f32 v4, s[4:5], v0, v0, 1.0
	v_rcp_f32_e32 v5, v4
	v_div_scale_f32 v6, vcc, 1.0, v0, 1.0
	v_mov_b32_e32 v177, v1
	v_fma_f32 v7, -v4, v5, 1.0
	v_fmac_f32_e32 v5, v7, v5
	v_mul_f32_e32 v7, v6, v5
	v_fma_f32 v8, -v4, v7, v6
	v_fmac_f32_e32 v7, v8, v5
	v_fma_f32 v4, -v4, v7, v6
	v_div_fmas_f32 v4, v4, v5, v7
	v_div_fixup_f32 v0, v4, v0, 1.0
	v_lshl_add_u64 v[2:3], v[2:3], 0, v[176:177]
	v_and_b32_e32 v4, 32, v206
	v_lshrrev_b32_e32 v4, 2, v4
	v_add_co_u32_e32 v2, vcc, v2, v4
	s_nop 1
	v_addc_co_u32_e32 v3, vcc, 0, v3, vcc
	v_mul_f32_e32 v64, v64, v0
	v_mul_f32_e32 v65, v65, v0
	v_mul_f32_e32 v66, v66, v0
	v_mul_f32_e32 v67, v67, v0
	v_mul_f32_e32 v68, v68, v0
	v_mul_f32_e32 v69, v69, v0
	v_mul_f32_e32 v70, v70, v0
	v_mul_f32_e32 v71, v71, v0
	v_cvt_pk_bf16_f32 v64, v64, v65
	v_cvt_pk_bf16_f32 v65, v66, v67
	v_cvt_pk_bf16_f32 v66, v68, v69
	v_cvt_pk_bf16_f32 v67, v70, v71
	s_nop 1
	v_permlane32_swap_b32 v64, v66
	v_permlane32_swap_b32 v65, v67
	global_store_dwordx4 v[2:3], v[64:67], off
	v_mul_f32_e32 v72, v72, v0
	v_mul_f32_e32 v73, v73, v0
	v_mul_f32_e32 v74, v74, v0
	v_mul_f32_e32 v75, v75, v0
	v_mul_f32_e32 v76, v76, v0
	v_mul_f32_e32 v77, v77, v0
	v_mul_f32_e32 v78, v78, v0
	v_mul_f32_e32 v79, v79, v0
	v_cvt_pk_bf16_f32 v72, v72, v73
	v_cvt_pk_bf16_f32 v73, v74, v75
	v_cvt_pk_bf16_f32 v74, v76, v77
	v_cvt_pk_bf16_f32 v75, v78, v79
	s_nop 1
	v_permlane32_swap_b32 v72, v74
	v_permlane32_swap_b32 v73, v75
	global_store_dwordx4 v[2:3], v[72:75], off offset:32
	v_mul_f32_e32 v48, v48, v0
	v_mul_f32_e32 v49, v49, v0
	v_mul_f32_e32 v50, v50, v0
	v_mul_f32_e32 v51, v51, v0
	v_mul_f32_e32 v52, v52, v0
	v_mul_f32_e32 v53, v53, v0
	v_mul_f32_e32 v54, v54, v0
	v_mul_f32_e32 v55, v55, v0
	v_cvt_pk_bf16_f32 v48, v48, v49
	v_cvt_pk_bf16_f32 v49, v50, v51
	v_cvt_pk_bf16_f32 v50, v52, v53
	v_cvt_pk_bf16_f32 v51, v54, v55
	s_nop 1
	v_permlane32_swap_b32 v48, v50
	v_permlane32_swap_b32 v49, v51
	global_store_dwordx4 v[2:3], v[48:51], off offset:64
	v_mul_f32_e32 v56, v56, v0
	v_mul_f32_e32 v57, v57, v0
	v_mul_f32_e32 v58, v58, v0
	v_mul_f32_e32 v59, v59, v0
	v_mul_f32_e32 v60, v60, v0
	v_mul_f32_e32 v61, v61, v0
	v_mul_f32_e32 v62, v62, v0
	v_mul_f32_e32 v63, v63, v0
	v_cvt_pk_bf16_f32 v56, v56, v57
	v_cvt_pk_bf16_f32 v57, v58, v59
	v_cvt_pk_bf16_f32 v58, v60, v61
	v_cvt_pk_bf16_f32 v59, v62, v63
	s_nop 1
	v_permlane32_swap_b32 v56, v58
	v_permlane32_swap_b32 v57, v59
	global_store_dwordx4 v[2:3], v[56:59], off offset:96
	v_mul_f32_e32 v32, v32, v0
	v_mul_f32_e32 v33, v33, v0
	v_mul_f32_e32 v34, v34, v0
	v_mul_f32_e32 v35, v35, v0
	v_mul_f32_e32 v36, v36, v0
	v_mul_f32_e32 v37, v37, v0
	v_mul_f32_e32 v38, v38, v0
	v_mul_f32_e32 v39, v39, v0
	v_cvt_pk_bf16_f32 v32, v32, v33
	v_cvt_pk_bf16_f32 v33, v34, v35
	v_cvt_pk_bf16_f32 v34, v36, v37
	v_cvt_pk_bf16_f32 v35, v38, v39
	s_nop 1
	v_permlane32_swap_b32 v32, v34
	v_permlane32_swap_b32 v33, v35
	global_store_dwordx4 v[2:3], v[32:35], off offset:128
	v_mul_f32_e32 v40, v40, v0
	v_mul_f32_e32 v41, v41, v0
	v_mul_f32_e32 v42, v42, v0
	v_mul_f32_e32 v43, v43, v0
	v_mul_f32_e32 v44, v44, v0
	v_mul_f32_e32 v45, v45, v0
	v_mul_f32_e32 v46, v46, v0
	v_mul_f32_e32 v47, v47, v0
	v_cvt_pk_bf16_f32 v40, v40, v41
	v_cvt_pk_bf16_f32 v41, v42, v43
	v_cvt_pk_bf16_f32 v42, v44, v45
	v_cvt_pk_bf16_f32 v43, v46, v47
	s_nop 1
	v_permlane32_swap_b32 v40, v42
	v_permlane32_swap_b32 v41, v43
	global_store_dwordx4 v[2:3], v[40:43], off offset:160
	v_mul_f32_e32 v16, v16, v0
	v_mul_f32_e32 v17, v17, v0
	v_mul_f32_e32 v18, v18, v0
	v_mul_f32_e32 v19, v19, v0
	v_mul_f32_e32 v20, v20, v0
	v_mul_f32_e32 v21, v21, v0
	v_mul_f32_e32 v22, v22, v0
	v_mul_f32_e32 v23, v23, v0
	v_cvt_pk_bf16_f32 v16, v16, v17
	v_cvt_pk_bf16_f32 v17, v18, v19
	v_cvt_pk_bf16_f32 v18, v20, v21
	v_cvt_pk_bf16_f32 v19, v22, v23
	s_nop 1
	v_permlane32_swap_b32 v16, v18
	v_permlane32_swap_b32 v17, v19
	global_store_dwordx4 v[2:3], v[16:19], off offset:192
	v_mul_f32_e32 v24, v24, v0
	v_mul_f32_e32 v25, v25, v0
	v_mul_f32_e32 v26, v26, v0
	v_mul_f32_e32 v27, v27, v0
	v_mul_f32_e32 v28, v28, v0
	v_mul_f32_e32 v29, v29, v0
	v_mul_f32_e32 v30, v30, v0
	v_mul_f32_e32 v31, v31, v0
	v_cvt_pk_bf16_f32 v24, v24, v25
	v_cvt_pk_bf16_f32 v25, v26, v27
	v_cvt_pk_bf16_f32 v26, v28, v29
	v_cvt_pk_bf16_f32 v27, v30, v31
	s_nop 1
	v_permlane32_swap_b32 v24, v26
	v_permlane32_swap_b32 v25, v27
	global_store_dwordx4 v[2:3], v[24:27], off offset:224
	s_waitcnt vmcnt(63) expcnt(7) lgkmcnt(15)
	s_barrier

; __device__ __forceinline__ unsigned cvt_pk_bf16(float lo, float hi) { unsigned r; asm volatile("v_cvt_pk_bf16_f32 %0, %1, %2" : "=v"(r) : "v"(lo), "v"(hi)); return r; }
; __device__ __forceinline__ void attn_na(unsigned char* lds, const int unit, const bf16_t* __restrict__ QKG, const bf16_t* __restrict__ Vt, bf16_t* __restrict__ Oout, const float* __restrict__ btab) {
;     ...
;     const float lt = l_run + __shfl_xor(l_run, 32), inv = 1.0f / lt;
;     bf16_t* op = Oout + (size_t)(b * SEQ + qtok) * 1024 + 128 * hd + 4 * hi;
; #pragma unroll
;     for (int db = 0; db < 4; ++db)
; #pragma unroll
;         for (int rg = 0; rg < 4; ++rg) { u32x2 w; w.x = cvt_pk_bf16(o[db][4 * rg] * inv, o[db][4 * rg + 1] * inv); w.y = cvt_pk_bf16(o[db][4 * rg + 2] * inv, o[db][4 * rg + 3] * inv);
;             *(u32x2*)(op + 32 * db + 8 * rg) = w; }
.LBB0_605:
	v_and_b32_e32 v67, 64, v206
	v_xor_b32_e32 v0, 32, v206
	v_add_u32_e32 v67, 64, v67
	v_cmp_lt_i32_e32 vcc, v0, v67
	s_lshl_b32 s60, s5, 1
	v_mov_b32_e32 v151, v1
	v_cndmask_b32_e32 v0, v206, v0, vcc
	v_lshlrev_b32_e32 v0, 2, v0
	ds_bpermute_b32 v0, v0, v66
	s_waitcnt lgkmcnt(0)
	v_add_f32_e32 v0, v66, v0
	v_div_scale_f32 v68, s[0:1], v0, v0, 1.0
	v_rcp_f32_e32 v69, v68
	v_div_scale_f32 v70, vcc, 1.0, v0, 1.0
	v_lshlrev_b64 v[66:67], 11, v[148:149]
	v_fma_f32 v71, -v68, v69, 1.0
	v_fmac_f32_e32 v69, v71, v69
	v_mul_f32_e32 v71, v70, v69
	v_fma_f32 v72, -v68, v71, v70
	v_fmac_f32_e32 v71, v72, v69
	v_fma_f32 v68, -v68, v71, v70
	v_div_fmas_f32 v68, v68, v69, v71
	v_div_fixup_f32 v0, v68, v0, 1.0
	v_lshl_add_u64 v[66:67], s[62:63], 0, v[66:67]
	v_lshl_add_u64 v[66:67], v[66:67], 0, s[60:61]
	v_lshl_add_u64 v[66:67], v[66:67], 0, v[150:151]
	v_and_b32_e32 v68, 32, v206
	v_lshrrev_b32_e32 v68, 2, v68
	v_add_co_u32_e32 v66, vcc, v66, v68
	s_nop 1
	v_addc_co_u32_e32 v67, vcc, 0, v67, vcc
	v_mul_f32_e32 v50, v50, v0
	v_mul_f32_e32 v51, v51, v0
	v_mul_f32_e32 v52, v52, v0
	v_mul_f32_e32 v53, v53, v0
	v_mul_f32_e32 v54, v54, v0
	v_mul_f32_e32 v55, v55, v0
	v_mul_f32_e32 v56, v56, v0
	v_mul_f32_e32 v57, v57, v0
	v_cvt_pk_bf16_f32 v50, v50, v51
	v_cvt_pk_bf16_f32 v51, v52, v53
	v_cvt_pk_bf16_f32 v52, v54, v55
	v_cvt_pk_bf16_f32 v53, v56, v57
	s_nop 1
	v_permlane32_swap_b32 v50, v52
	v_permlane32_swap_b32 v51, v53
	global_store_dwordx4 v[66:67], v[50:53], off
	v_mul_f32_e32 v58, v58, v0
	v_mul_f32_e32 v59, v59, v0
	v_mul_f32_e32 v60, v60, v0
	v_mul_f32_e32 v61, v61, v0
	v_mul_f32_e32 v62, v62, v0
	v_mul_f32_e32 v63, v63, v0
	v_mul_f32_e32 v64, v64, v0
	v_mul_f32_e32 v65, v65, v0
	v_cvt_pk_bf16_f32 v58, v58, v59
	v_cvt_pk_bf16_f32 v59, v60, v61
	v_cvt_pk_bf16_f32 v60, v62, v63
	v_cvt_pk_bf16_f32 v61, v64, v65
	s_nop 1
	v_permlane32_swap_b32 v58, v60
	v_permlane32_swap_b32 v59, v61
	global_store_dwordx4 v[66:67], v[58:61], off offset:32
	v_mul_f32_e32 v34, v34, v0
	v_mul_f32_e32 v35, v35, v0
	v_mul_f32_e32 v36, v36, v0
	v_mul_f32_e32 v37, v37, v0
	v_mul_f32_e32 v38, v38, v0
	v_mul_f32_e32 v39, v39, v0
	v_mul_f32_e32 v40, v40, v0
	v_mul_f32_e32 v41, v41, v0
	v_cvt_pk_bf16_f32 v34, v34, v35
	v_cvt_pk_bf16_f32 v35, v36, v37
	v_cvt_pk_bf16_f32 v36, v38, v39
	v_cvt_pk_bf16_f32 v37, v40, v41
	s_nop 1
	v_permlane32_swap_b32 v34, v36
	v_permlane32_swap_b32 v35, v37
	global_store_dwordx4 v[66:67], v[34:37], off offset:64
	v_mul_f32_e32 v42, v42, v0
	v_mul_f32_e32 v43, v43, v0
	v_mul_f32_e32 v44, v44, v0
	v_mul_f32_e32 v45, v45, v0
	v_mul_f32_e32 v46, v46, v0
	v_mul_f32_e32 v47, v47, v0
	v_mul_f32_e32 v48, v48, v0
	v_mul_f32_e32 v49, v49, v0
	v_cvt_pk_bf16_f32 v42, v42, v43
	v_cvt_pk_bf16_f32 v43, v44, v45
	v_cvt_pk_bf16_f32 v44, v46, v47
	v_cvt_pk_bf16_f32 v45, v48, v49
	s_nop 1
	v_permlane32_swap_b32 v42, v44
	v_permlane32_swap_b32 v43, v45
	global_store_dwordx4 v[66:67], v[42:45], off offset:96
	v_mul_f32_e32 v18, v18, v0
	v_mul_f32_e32 v19, v19, v0
	v_mul_f32_e32 v20, v20, v0
	v_mul_f32_e32 v21, v21, v0
	v_mul_f32_e32 v22, v22, v0
	v_mul_f32_e32 v23, v23, v0
	v_mul_f32_e32 v24, v24, v0
	v_mul_f32_e32 v25, v25, v0
	v_cvt_pk_bf16_f32 v18, v18, v19
	v_cvt_pk_bf16_f32 v19, v20, v21
	v_cvt_pk_bf16_f32 v20, v22, v23
	v_cvt_pk_bf16_f32 v21, v24, v25
	s_nop 1
	v_permlane32_swap_b32 v18, v20
	v_permlane32_swap_b32 v19, v21
	global_store_dwordx4 v[66:67], v[18:21], off offset:128
	v_mul_f32_e32 v26, v26, v0
	v_mul_f32_e32 v27, v27, v0
	v_mul_f32_e32 v28, v28, v0
	v_mul_f32_e32 v29, v29, v0
	v_mul_f32_e32 v30, v30, v0
	v_mul_f32_e32 v31, v31, v0
	v_mul_f32_e32 v32, v32, v0
	v_mul_f32_e32 v33, v33, v0
	v_cvt_pk_bf16_f32 v26, v26, v27
	v_cvt_pk_bf16_f32 v27, v28, v29
	v_cvt_pk_bf16_f32 v28, v30, v31
	v_cvt_pk_bf16_f32 v29, v32, v33
	s_nop 1
	v_permlane32_swap_b32 v26, v28
	v_permlane32_swap_b32 v27, v29
	global_store_dwordx4 v[66:67], v[26:29], off offset:160
	v_mul_f32_e32 v2, v2, v0
	v_mul_f32_e32 v3, v3, v0
	v_mul_f32_e32 v4, v4, v0
	v_mul_f32_e32 v5, v5, v0
	v_mul_f32_e32 v6, v6, v0
	v_mul_f32_e32 v7, v7, v0
	v_mul_f32_e32 v8, v8, v0
	v_mul_f32_e32 v9, v9, v0
	v_cvt_pk_bf16_f32 v2, v2, v3
	v_cvt_pk_bf16_f32 v3, v4, v5
	v_cvt_pk_bf16_f32 v4, v6, v7
	v_cvt_pk_bf16_f32 v5, v8, v9
	s_nop 1
	v_permlane32_swap_b32 v2, v4
	v_permlane32_swap_b32 v3, v5
	global_store_dwordx4 v[66:67], v[2:5], off offset:192
	v_mul_f32_e32 v10, v10, v0
	v_mul_f32_e32 v11, v11, v0
	v_mul_f32_e32 v12, v12, v0
	v_mul_f32_e32 v13, v13, v0
	v_mul_f32_e32 v14, v14, v0
	v_mul_f32_e32 v15, v15, v0
	v_mul_f32_e32 v16, v16, v0
	v_mul_f32_e32 v17, v17, v0
	v_cvt_pk_bf16_f32 v10, v10, v11
	v_cvt_pk_bf16_f32 v11, v12, v13
	v_cvt_pk_bf16_f32 v12, v14, v15
	v_cvt_pk_bf16_f32 v13, v16, v17
	s_nop 1
	v_permlane32_swap_b32 v10, v12
	v_permlane32_swap_b32 v11, v13
	global_store_dwordx4 v[66:67], v[10:13], off offset:224
	s_waitcnt vmcnt(63) expcnt(7) lgkmcnt(15)
	s_barrier
